# v21: P2 prompt loops - chunk-total decay broadcast by ds_bpermute (was 2 readlane+2 mov+cndmask per channel), GLA 5th scan step fused into one v_add_f32_dpp
# baseline (speedup 1.0000x reference)
.LBB0_509:
	s_cmp_lt_i32 s92, 3
	s_cselect_b64 s[0:1], -1, 0
	s_and_b64 s[4:5], s[0:1], s[2:3]
	s_andn2_b64 vcc, exec, s[4:5]
	v_lshlrev_b32_e32 v178, 2, v1
	s_cbranch_vccnz .LBB0_666
	v_and_b32_e32 v244, 32, v1
	v_lshlrev_b32_e32 v244, 2, v244
	v_add_u32_e32 v244, 0x7c, v244
	v_mov_b32_e32 v179, 0
	v_lshl_add_u64 v[2:3], s[60:61], 0, v[178:179]
	v_add_co_u32_e32 v4, vcc, 0x1000, v2
	v_or_b32_e32 v8, 0x1000, v178
	s_nop 0
	v_addc_co_u32_e32 v5, vcc, 0, v3, vcc
	v_add_co_u32_e32 v6, vcc, 0x2000, v2
	v_or_b32_e32 v9, 0x2000, v178
	s_nop 0
	v_addc_co_u32_e32 v7, vcc, 0, v3, vcc
	v_or_b32_e32 v10, 0xc00, v1
	v_lshlrev_b32_e32 v11, 2, v10
	global_load_dword v12, v178, s[60:61]
	global_load_dword v13, v178, s[60:61] offset:2048
	s_nop 0
	global_load_dword v8, v8, s[60:61]
	s_nop 0
	global_load_dword v5, v[4:5], off offset:2048
	s_nop 0
	global_load_dword v9, v9, s[60:61]
	s_nop 0
	global_load_dword v6, v[6:7], off offset:2048
	s_nop 0
	global_load_dword v7, v11, s[60:61]
	s_movk_i32 s0, 0xe00
	v_add_u32_e32 v4, 0, v178
	v_cmp_gt_u32_e32 vcc, s0, v10
	s_waitcnt vmcnt(0)
	ds_write2st64_b32 v4, v12, v13 offset1:8
	ds_write2st64_b32 v4, v8, v5 offset0:16 offset1:24
	ds_write2st64_b32 v4, v9, v6 offset0:32 offset1:40
	ds_write_b32 v4, v7 offset:12288
	s_and_saveexec_b64 s[0:1], vcc
	s_cbranch_execz .LBB0_512
	v_add_co_u32_e32 v2, vcc, 0x3000, v2
	s_nop 1
	v_addc_co_u32_e32 v3, vcc, 0, v3, vcc
	global_load_dword v2, v[2:3], off offset:2048
	s_waitcnt vmcnt(0)
	ds_write_b32 v4, v2 offset:14336

.Lp2h_mid:
	ds_read_b128 v[46:49], v41
	ds_read_b128 v[52:55], v41 offset:16
	v_mul_f32_e64 v41, |v33|, s80
	v_exp_f32_e32 v80, v41
	v_mul_f32_e64 v41, |v32|, s80
	v_exp_f32_e32 v81, v41
	v_mul_f32_e64 v41, |v31|, s80
	v_exp_f32_e32 v82, v41
	v_mul_f32_e64 v41, |v30|, s80
	v_exp_f32_e32 v83, v41
	v_mul_f32_e64 v41, |v29|, s80
	v_exp_f32_e32 v84, v41
	v_mul_f32_e64 v41, |v28|, s80
	v_exp_f32_e32 v85, v41
	v_mul_f32_e64 v41, |v27|, s80
	v_exp_f32_e32 v86, v41
	v_mul_f32_e64 v41, |v26|, s80
	v_exp_f32_e32 v87, v41
	v_add_f32_e32 v41, 1.0, v80
	v_rcp_f32_e32 v88, v41
	v_add_f32_e32 v41, 1.0, v81
	v_rcp_f32_e32 v89, v41
	v_add_f32_e32 v41, 1.0, v82
	v_rcp_f32_e32 v90, v41
	v_add_f32_e32 v41, 1.0, v83
	v_rcp_f32_e32 v91, v41
	v_add_f32_e32 v41, 1.0, v84
	v_rcp_f32_e32 v92, v41
	v_add_f32_e32 v41, 1.0, v85
	v_rcp_f32_e32 v93, v41
	v_add_f32_e32 v41, 1.0, v86
	v_pk_mul_f32 v[80:81], v[80:81], v[88:89]
	v_cmp_nle_f32_e32 vcc, 0, v33
	v_rcp_f32_e32 v94, v41
	v_add_f32_e32 v41, 1.0, v87
	v_cndmask_b32_e32 v33, v80, v88, vcc
	s_waitcnt lgkmcnt(1)
	v_pk_add_f32 v[96:97], v[46:47], 1.0 op_sel_hi:[1,0] neg_lo:[1,0] neg_hi:[1,0]
	v_cmp_nle_f32_e64 s[0:1], 0, v32
	v_rcp_f32_e32 v95, v41
	v_mul_f32_e32 v41, v96, v33
	v_cndmask_b32_e64 v33, v89, v81, s[0:1]
	v_cndmask_b32_e32 v32, v88, v80, vcc
	v_cndmask_b32_e64 v51, v81, v89, s[0:1]
	v_pk_fma_f32 v[32:33], v[96:97], v[32:33], v[46:47]
	v_pk_mul_f32 v[46:47], v[82:83], v[90:91]
	v_cmp_nle_f32_e32 vcc, 0, v31
	v_cmp_nle_f32_e64 s[0:1], 0, v30
	v_pk_add_f32 v[80:81], v[48:49], 1.0 op_sel_hi:[1,0] neg_lo:[1,0] neg_hi:[1,0]
	v_cndmask_b32_e32 v31, v46, v90, vcc
	v_cndmask_b32_e32 v30, v90, v46, vcc
	v_cndmask_b32_e64 v46, v47, v91, s[0:1]
	v_mul_f32_e32 v56, v80, v31
	v_cndmask_b32_e64 v31, v91, v47, s[0:1]
	v_mul_f32_e32 v71, v81, v46
	v_pk_mul_f32 v[46:47], v[84:85], v[92:93]
	v_cmp_nle_f32_e32 vcc, 0, v29
	v_cmp_nle_f32_e64 s[0:1], 0, v28
	v_pk_fma_f32 v[30:31], v[80:81], v[30:31], v[48:49]
	v_cndmask_b32_e32 v29, v46, v92, vcc
	s_waitcnt lgkmcnt(0)
	v_pk_add_f32 v[48:49], v[52:53], 1.0 op_sel_hi:[1,0] neg_lo:[1,0] neg_hi:[1,0]
	v_cndmask_b32_e32 v28, v92, v46, vcc
	v_cndmask_b32_e64 v46, v47, v93, s[0:1]
	v_mul_f32_e32 v73, v48, v29
	v_cndmask_b32_e64 v29, v93, v47, s[0:1]
	v_mul_f32_e32 v75, v49, v46
	v_pk_mul_f32 v[46:47], v[86:87], v[94:95]
	v_cmp_nle_f32_e32 vcc, 0, v27
	v_pk_fma_f32 v[28:29], v[48:49], v[28:29], v[52:53]
	v_pk_add_f32 v[48:49], v[54:55], 1.0 op_sel_hi:[1,0] neg_lo:[1,0] neg_hi:[1,0]
	v_cndmask_b32_e32 v27, v46, v94, vcc
	v_cmp_nle_f32_e64 s[0:1], 0, v26
	v_mul_f32_e32 v77, v48, v27
	v_cndmask_b32_e32 v26, v94, v46, vcc
	v_cndmask_b32_e64 v27, v95, v47, s[0:1]
	v_cndmask_b32_e64 v52, v47, v95, s[0:1]
	v_and_b32_e32 v47, 0xffff0000, v42
	v_pk_fma_f32 v[26:27], v[48:49], v[26:27], v[54:55]
	v_mul_f32_e32 v48, 0xbfb8aa3b, v47
	v_exp_f32_e32 v48, v48
	v_mul_f32_e32 v79, v49, v52
	v_lshlrev_b32_e32 v46, 16, v42
	v_and_b32_e32 v49, 0xffff0000, v43
	v_add_f32_e32 v52, 1.0, v48
	v_lshlrev_b32_e32 v48, 16, v43
	v_mul_f32_e32 v43, 0xbfb8aa3b, v48
	v_mul_f32_e32 v42, 0xbfb8aa3b, v46
	v_exp_f32_e32 v53, v43
	v_mul_f32_e32 v43, 0xbfb8aa3b, v49
	v_exp_f32_e32 v42, v42
	v_exp_f32_e32 v54, v43
	v_rcp_f32_e32 v43, v52
	v_add_f32_e32 v52, 1.0, v53
	v_add_f32_e32 v42, 1.0, v42
	v_add_f32_e32 v53, 1.0, v54
	v_rcp_f32_e32 v42, v42
	v_rcp_f32_e32 v52, v52
	v_rcp_f32_e32 v53, v53
	v_cndmask_b32_e64 v32, 1.0, v32, s[42:43]
	v_pk_mul_f32 v[42:43], v[42:43], v[46:47]
	v_cndmask_b32_e64 v33, 1.0, v33, s[42:43]
	v_pk_mul_f32 v[46:47], v[52:53], v[48:49]
	v_cndmask_b32_e64 v30, 1.0, v30, s[42:43]
	v_cndmask_b32_e64 v31, 1.0, v31, s[42:43]
	v_mul_f32_dpp v32, v32, v32 row_shr:1 row_mask:0xf bank_mask:0xf
	v_cndmask_b32_e64 v28, 1.0, v28, s[42:43]
	v_cndmask_b32_e64 v29, 1.0, v29, s[42:43]
	v_mul_f32_dpp v33, v33, v33 row_shr:1 row_mask:0xf bank_mask:0xf
	v_cndmask_b32_e64 v26, 1.0, v26, s[42:43]
	v_cndmask_b32_e64 v27, 1.0, v27, s[42:43]
	v_mul_f32_dpp v30, v30, v30 row_shr:1 row_mask:0xf bank_mask:0xf
	v_and_b32_e32 v55, 0xffff0000, v44
	v_mul_f32_e32 v80, 0xbfb8aa3b, v55
	v_mul_f32_dpp v31, v31, v31 row_shr:1 row_mask:0xf bank_mask:0xf
	v_exp_f32_e32 v80, v80
	v_lshlrev_b32_e32 v54, 16, v44
	v_mul_f32_dpp v28, v28, v28 row_shr:1 row_mask:0xf bank_mask:0xf
	v_add_f32_e32 v82, 1.0, v80
	v_lshlrev_b32_e32 v80, 16, v45
	v_mul_f32_dpp v29, v29, v29 row_shr:1 row_mask:0xf bank_mask:0xf
	v_and_b32_e32 v81, 0xffff0000, v45
	v_mul_f32_e32 v45, 0xbfb8aa3b, v80
	v_mul_f32_dpp v26, v26, v26 row_shr:1 row_mask:0xf bank_mask:0xf
	v_mul_f32_e32 v44, 0xbfb8aa3b, v54
	v_exp_f32_e32 v83, v45
	v_mul_f32_dpp v27, v27, v27 row_shr:1 row_mask:0xf bank_mask:0xf
	v_mul_f32_e32 v45, 0xbfb8aa3b, v81
	v_exp_f32_e32 v44, v44
	v_mul_f32_dpp v32, v32, v32 row_shr:2 row_mask:0xf bank_mask:0xf
	v_exp_f32_e32 v84, v45
	v_add_f32_e32 v44, 1.0, v44
	v_mul_f32_dpp v33, v33, v33 row_shr:2 row_mask:0xf bank_mask:0xf
	v_rcp_f32_e32 v45, v82
	v_add_f32_e32 v82, 1.0, v83
	v_mul_f32_dpp v30, v30, v30 row_shr:2 row_mask:0xf bank_mask:0xf
	v_add_f32_e32 v83, 1.0, v84
	v_rcp_f32_e32 v44, v44
	v_mul_f32_dpp v31, v31, v31 row_shr:2 row_mask:0xf bank_mask:0xf
	v_rcp_f32_e32 v82, v82
	v_rcp_f32_e32 v83, v83
	v_mul_f32_dpp v28, v28, v28 row_shr:2 row_mask:0xf bank_mask:0xf
	v_pk_mul_f32 v[44:45], v[44:45], v[54:55]
	v_pk_mul_f32 v[48:49], v[82:83], v[80:81]
	v_mul_f32_dpp v29, v29, v29 row_shr:2 row_mask:0xf bank_mask:0xf
	v_mul_f32_e32 v51, v97, v51
	v_cndmask_b32_e64 v41, 0, v41, s[42:43]
	v_mul_f32_dpp v26, v26, v26 row_shr:2 row_mask:0xf bank_mask:0xf
	v_cndmask_b32_e64 v51, 0, v51, s[42:43]
	v_cndmask_b32_e64 v56, 0, v56, s[42:43]
	v_mul_f32_dpp v27, v27, v27 row_shr:2 row_mask:0xf bank_mask:0xf
	v_cndmask_b32_e64 v71, 0, v71, s[42:43]
	v_cndmask_b32_e64 v73, 0, v73, s[42:43]
	v_mul_f32_dpp v32, v32, v32 row_shr:4 row_mask:0xf bank_mask:0xf
	v_cndmask_b32_e64 v75, 0, v75, s[42:43]
	v_cndmask_b32_e64 v77, 0, v77, s[42:43]
	v_mul_f32_dpp v33, v33, v33 row_shr:4 row_mask:0xf bank_mask:0xf
	v_cndmask_b32_e64 v79, 0, v79, s[42:43]
	v_cndmask_b32_e64 v49, 0, v49, s[42:43]
	v_mul_f32_dpp v30, v30, v30 row_shr:4 row_mask:0xf bank_mask:0xf
	v_cndmask_b32_e64 v48, 0, v48, s[42:43]
	v_cndmask_b32_e64 v47, 0, v47, s[42:43]
	v_mul_f32_dpp v31, v31, v31 row_shr:4 row_mask:0xf bank_mask:0xf
	v_cndmask_b32_e64 v46, 0, v46, s[42:43]
	v_cndmask_b32_e64 v45, 0, v45, s[42:43]
	v_mul_f32_dpp v28, v28, v28 row_shr:4 row_mask:0xf bank_mask:0xf
	v_cndmask_b32_e64 v44, 0, v44, s[42:43]
	v_cndmask_b32_e64 v43, 0, v43, s[42:43]
	v_mul_f32_dpp v29, v29, v29 row_shr:4 row_mask:0xf bank_mask:0xf
	v_cndmask_b32_e64 v42, 0, v42, s[42:43]
	s_nop 0
	v_mul_f32_dpp v26, v26, v26 row_shr:4 row_mask:0xf bank_mask:0xf
	v_mul_f32_dpp v27, v27, v27 row_shr:4 row_mask:0xf bank_mask:0xf
	v_mul_f32_dpp v32, v32, v32 row_shr:8 row_mask:0xf bank_mask:0xf
	v_mul_f32_dpp v33, v33, v33 row_shr:8 row_mask:0xf bank_mask:0xf
	v_mul_f32_dpp v30, v30, v30 row_shr:8 row_mask:0xf bank_mask:0xf
	v_mul_f32_dpp v31, v31, v31 row_shr:8 row_mask:0xf bank_mask:0xf
	v_mul_f32_dpp v28, v28, v28 row_shr:8 row_mask:0xf bank_mask:0xf
	v_mul_f32_dpp v29, v29, v29 row_shr:8 row_mask:0xf bank_mask:0xf
	v_mul_f32_dpp v26, v26, v26 row_shr:8 row_mask:0xf bank_mask:0xf
	v_mul_f32_dpp v27, v27, v27 row_shr:8 row_mask:0xf bank_mask:0xf
	v_mul_f32_dpp v32, v32, v32 row_bcast:15 row_mask:0xa bank_mask:0xf
	v_mul_f32_dpp v33, v33, v33 row_bcast:15 row_mask:0xa bank_mask:0xf
	v_max_f32_e32 v53, 0x554ad2e, v33
	v_rcp_f32_e32 v85, v53
	v_mul_f32_dpp v30, v30, v30 row_bcast:15 row_mask:0xa bank_mask:0xf
	v_max_f32_e32 v54, 0x554ad2e, v30
	v_rcp_f32_e32 v86, v54
	v_mul_f32_dpp v31, v31, v31 row_bcast:15 row_mask:0xa bank_mask:0xf
	v_max_f32_e32 v55, 0x554ad2e, v31
	v_rcp_f32_e32 v87, v55
	v_mul_f32_dpp v28, v28, v28 row_bcast:15 row_mask:0xa bank_mask:0xf
	v_max_f32_e32 v80, 0x554ad2e, v28
	v_rcp_f32_e32 v88, v80
	v_mul_f32_dpp v29, v29, v29 row_bcast:15 row_mask:0xa bank_mask:0xf
	v_max_f32_e32 v81, 0x554ad2e, v29
	v_rcp_f32_e32 v89, v81
	v_mul_f32_dpp v26, v26, v26 row_bcast:15 row_mask:0xa bank_mask:0xf
	v_max_f32_e32 v82, 0x554ad2e, v26
	v_rcp_f32_e32 v90, v82
	v_mul_f32_dpp v27, v27, v27 row_bcast:15 row_mask:0xa bank_mask:0xf
	v_max_f32_e32 v52, 0x554ad2e, v32
	v_max_f32_e32 v83, 0x554ad2e, v27
	ds_bpermute_b32 v26, v244, v52
	ds_bpermute_b32 v27, v244, v53
	ds_bpermute_b32 v28, v244, v54
	ds_bpermute_b32 v29, v244, v55
	ds_bpermute_b32 v30, v244, v80
	ds_bpermute_b32 v31, v244, v81
	ds_bpermute_b32 v32, v244, v82
	ds_bpermute_b32 v33, v244, v83
	v_rcp_f32_e32 v84, v52
	v_rcp_f32_e32 v91, v83
	v_mul_f32_e32 v41, v41, v84
	v_pk_mul_f32 v[42:43], v[42:43], v[52:53]
	v_mul_f32_e32 v51, v51, v85
	v_mul_f32_e32 v53, v56, v86
	v_pk_mul_f32 v[46:47], v[46:47], v[54:55]
	v_mul_f32_e32 v54, v71, v87
	v_mul_f32_e32 v71, v73, v88
	v_pk_mul_f32 v[44:45], v[44:45], v[80:81]
	v_mul_f32_e32 v75, v75, v89
	v_mul_f32_e32 v77, v77, v90
	v_pk_mul_f32 v[48:49], v[48:49], v[82:83]
	v_mul_f32_e32 v79, v79, v91
	v_cvt_pk_bf16_f32 v42, v42, v43
	v_cvt_pk_bf16_f32 v43, v46, v47
	v_cvt_pk_bf16_f32 v44, v44, v45
	v_cvt_pk_bf16_f32 v45, v48, v49
	v_cvt_pk_bf16_f32 v46, v41, v51
	v_cvt_pk_bf16_f32 v47, v53, v54
	v_cvt_pk_bf16_f32 v48, v71, v75
	v_cvt_pk_bf16_f32 v49, v77, v79
	s_nop 1
	v_mfma_f32_32x32x16_bf16 v[2:17], v[46:49], v[42:45], v[2:17]
	s_waitcnt lgkmcnt(0)
	v_mul_f32_e32 v84, v41, v26
	v_xor_b32_e32 v41, v39, v65
	v_mul_f32_e32 v52, v51, v27
	v_lshl_add_u32 v41, v41, 4, v148
	v_mul_f32_e32 v56, v53, v28
	v_mul_f32_e32 v55, v54, v29
	ds_write_b128 v41, v[42:45] offset:20480
	v_cvt_pk_bf16_f32 v41, v84, v52
	v_mul_f32_e32 v73, v71, v30
	v_mul_f32_e32 v80, v75, v31
	ds_write_b16 v40, v41
	ds_write_b16_d16_hi v40, v41 offset:64
	v_cvt_pk_bf16_f32 v41, v56, v55
	v_mul_f32_e32 v81, v77, v32
	v_mul_f32_e32 v82, v79, v33
	ds_write_b16 v40, v41 offset:128
	ds_write_b16_d16_hi v40, v41 offset:192
	v_cvt_pk_bf16_f32 v41, v73, v80
	ds_write_b16 v40, v41 offset:256
	ds_write_b16_d16_hi v40, v41 offset:320
	v_cvt_pk_bf16_f32 v41, v81, v82
	ds_write_b16 v40, v41 offset:384
	ds_write_b16_d16_hi v40, v41 offset:448
	s_and_saveexec_b64 s[0:1], s[4:5]
	s_cbranch_execz .LBB0_527
	v_add_u32_e32 v41, s17, v183
	ds_write_b128 v41, v[26:29]
	ds_write_b128 v41, v[30:33] offset:16
	s_branch .LBB0_527

.Lp2g_mid:
	s_xor_b32 s99, s99, 1
	ds_read_b128 v[124:127], v75 offset:16384
	ds_read_b128 v[128:131], v75 offset:16400
	ds_read_b128 v[188:191], v75
	ds_read_b128 v[192:195], v75 offset:16
	ds_read_b128 v[196:199], v75 offset:1024
	ds_read_b128 v[200:203], v75 offset:1040
	ds_read_b128 v[204:207], v75 offset:2048
	ds_read_b128 v[210:213], v75 offset:2064
	ds_read_b128 v[214:217], v75 offset:3072
	ds_read_b128 v[218:221], v75 offset:3088
	s_waitcnt lgkmcnt(7)
	v_pk_fma_f32 v[126:127], v[52:53], v[190:191], v[126:127]
	v_pk_fma_f32 v[124:125], v[50:51], v[188:189], v[124:125]
	s_waitcnt lgkmcnt(6)
	v_pk_fma_f32 v[130:131], v[52:53], v[194:195], v[130:131]
	v_pk_fma_f32 v[128:129], v[50:51], v[192:193], v[128:129]
	s_waitcnt lgkmcnt(5)
	v_pk_fma_f32 v[126:127], v[28:29], v[198:199], v[126:127]
	v_pk_fma_f32 v[124:125], v[54:55], v[196:197], v[124:125]
	s_waitcnt lgkmcnt(4)
	v_pk_fma_f32 v[130:131], v[28:29], v[202:203], v[130:131]
	v_pk_fma_f32 v[128:129], v[54:55], v[200:201], v[128:129]
	s_waitcnt lgkmcnt(3)
	v_pk_fma_f32 v[126:127], v[82:83], v[206:207], v[126:127]
	v_pk_fma_f32 v[124:125], v[80:81], v[204:205], v[124:125]
	s_waitcnt lgkmcnt(2)
	v_pk_fma_f32 v[130:131], v[82:83], v[212:213], v[130:131]
	v_pk_fma_f32 v[128:129], v[80:81], v[210:211], v[128:129]
	s_waitcnt lgkmcnt(1)
	v_pk_fma_f32 v[132:133], v[30:31], v[216:217], v[126:127]
	v_pk_fma_f32 v[214:215], v[84:85], v[214:215], v[124:125]
	s_waitcnt lgkmcnt(0)
	v_pk_fma_f32 v[216:217], v[30:31], v[220:221], v[130:131]
	v_pk_fma_f32 v[218:219], v[84:85], v[218:219], v[128:129]
	ds_read_b128 v[124:127], v75 offset:4096
	ds_read_b128 v[128:131], v75 offset:4112
	ds_read_b128 v[188:191], v75 offset:5120
	ds_read_b128 v[192:195], v75 offset:5136
	ds_read_b128 v[196:199], v75 offset:6144
	ds_read_b128 v[200:203], v75 offset:6160
	ds_read_b128 v[204:207], v75 offset:7168
	ds_read_b128 v[210:213], v75 offset:7184
	s_waitcnt lgkmcnt(7)
	v_pk_fma_f32 v[126:127], v[88:89], v[126:127], v[132:133]
	v_pk_fma_f32 v[124:125], v[86:87], v[124:125], v[214:215]
	s_waitcnt lgkmcnt(6)
	v_pk_fma_f32 v[130:131], v[88:89], v[130:131], v[216:217]
	v_pk_fma_f32 v[128:129], v[86:87], v[128:129], v[218:219]
	s_waitcnt lgkmcnt(5)
	v_pk_fma_f32 v[126:127], v[24:25], v[190:191], v[126:127]
	v_pk_fma_f32 v[124:125], v[90:91], v[188:189], v[124:125]
	s_waitcnt lgkmcnt(4)
	v_pk_fma_f32 v[130:131], v[24:25], v[194:195], v[130:131]
	v_pk_fma_f32 v[128:129], v[90:91], v[192:193], v[128:129]
	s_waitcnt lgkmcnt(3)
	v_pk_fma_f32 v[126:127], v[94:95], v[198:199], v[126:127]
	v_pk_fma_f32 v[124:125], v[92:93], v[196:197], v[124:125]
	s_waitcnt lgkmcnt(2)
	v_pk_fma_f32 v[130:131], v[94:95], v[202:203], v[130:131]
	v_pk_fma_f32 v[128:129], v[92:93], v[200:201], v[128:129]
	s_waitcnt lgkmcnt(1)
	v_pk_fma_f32 v[132:133], v[26:27], v[206:207], v[126:127]
	v_pk_fma_f32 v[214:215], v[96:97], v[204:205], v[124:125]
	s_waitcnt lgkmcnt(0)
	v_pk_fma_f32 v[216:217], v[26:27], v[212:213], v[130:131]
	v_pk_fma_f32 v[218:219], v[96:97], v[210:211], v[128:129]
	ds_read_b128 v[124:127], v75 offset:8192
	ds_read_b128 v[128:131], v75 offset:8208
	ds_read_b128 v[188:191], v75 offset:9216
	ds_read_b128 v[192:195], v75 offset:9232
	ds_read_b128 v[196:199], v75 offset:10240
	ds_read_b128 v[200:203], v75 offset:10256
	ds_read_b128 v[204:207], v75 offset:11264
	ds_read_b128 v[210:213], v75 offset:11280
	s_waitcnt lgkmcnt(7)
	v_pk_fma_f32 v[126:127], v[100:101], v[126:127], v[132:133]
	v_pk_fma_f32 v[124:125], v[98:99], v[124:125], v[214:215]
	s_waitcnt lgkmcnt(6)
	v_pk_fma_f32 v[130:131], v[100:101], v[130:131], v[216:217]
	v_pk_fma_f32 v[128:129], v[98:99], v[128:129], v[218:219]
	s_waitcnt lgkmcnt(5)
	v_pk_fma_f32 v[126:127], v[20:21], v[190:191], v[126:127]
	v_pk_fma_f32 v[124:125], v[102:103], v[188:189], v[124:125]
	s_waitcnt lgkmcnt(4)
	v_pk_fma_f32 v[130:131], v[20:21], v[194:195], v[130:131]
	v_pk_fma_f32 v[128:129], v[102:103], v[192:193], v[128:129]
	s_waitcnt lgkmcnt(3)
	v_pk_fma_f32 v[126:127], v[106:107], v[198:199], v[126:127]
	v_pk_fma_f32 v[124:125], v[104:105], v[196:197], v[124:125]
	s_waitcnt lgkmcnt(2)
	v_pk_fma_f32 v[130:131], v[106:107], v[202:203], v[130:131]
	v_pk_fma_f32 v[128:129], v[104:105], v[200:201], v[128:129]
	s_waitcnt lgkmcnt(1)
	v_pk_fma_f32 v[132:133], v[22:23], v[206:207], v[126:127]
	v_pk_fma_f32 v[214:215], v[108:109], v[204:205], v[124:125]
	s_waitcnt lgkmcnt(0)
	v_pk_fma_f32 v[216:217], v[22:23], v[212:213], v[130:131]
	v_pk_fma_f32 v[218:219], v[108:109], v[210:211], v[128:129]
	ds_read_b128 v[124:127], v75 offset:12288
	ds_read_b128 v[128:131], v75 offset:12304
	ds_read_b128 v[188:191], v75 offset:13312
	ds_read_b128 v[192:195], v75 offset:13328
	ds_read_b128 v[196:199], v75 offset:14336
	ds_read_b128 v[200:203], v75 offset:14352
	ds_read_b128 v[204:207], v75 offset:15360
	ds_read_b128 v[210:213], v75 offset:15376
	s_waitcnt lgkmcnt(7)
	v_pk_fma_f32 v[124:125], v[110:111], v[124:125], v[214:215]
	s_waitcnt lgkmcnt(6)
	v_pk_fma_f32 v[130:131], v[112:113], v[130:131], v[216:217]
	s_waitcnt lgkmcnt(5)
	v_pk_fma_f32 v[124:125], v[114:115], v[188:189], v[124:125]
	v_pk_fma_f32 v[126:127], v[112:113], v[126:127], v[132:133]
	s_waitcnt lgkmcnt(4)
	v_pk_fma_f32 v[130:131], v[116:117], v[194:195], v[130:131]
	s_waitcnt lgkmcnt(3)
	v_pk_fma_f32 v[124:125], v[118:119], v[196:197], v[124:125]
	v_pk_fma_f32 v[128:129], v[110:111], v[128:129], v[218:219]
	v_pk_fma_f32 v[126:127], v[116:117], v[190:191], v[126:127]
	s_waitcnt lgkmcnt(2)
	v_pk_fma_f32 v[132:133], v[120:121], v[202:203], v[130:131]
	s_waitcnt lgkmcnt(1)
	v_pk_fma_f32 v[130:131], v[122:123], v[204:205], v[124:125]
	v_pk_fma_f32 v[128:129], v[114:115], v[192:193], v[128:129]
	v_pk_fma_f32 v[126:127], v[120:121], v[198:199], v[126:127]
	v_mul_f32_e64 v75, |v130|, s80
	v_pk_fma_f32 v[188:189], v[118:119], v[200:201], v[128:129]
	v_pk_fma_f32 v[128:129], v[18:19], v[206:207], v[126:127]
	v_exp_f32_e32 v75, v75
	s_waitcnt lgkmcnt(0)
	v_pk_fma_f32 v[124:125], v[18:19], v[212:213], v[132:133]
	v_pk_fma_f32 v[126:127], v[122:123], v[210:211], v[188:189]
	v_mul_f32_e64 v132, |v129|, s80
	v_exp_f32_e32 v187, v132
	v_mul_f32_e64 v132, |v126|, s80
	v_exp_f32_e32 v190, v132
	v_mul_f32_e64 v132, |v127|, s80
	v_exp_f32_e32 v191, v132
	v_mul_f32_e64 v132, |v124|, s80
	v_add_f32_e32 v75, 1.0, v75
	v_exp_f32_e32 v192, v132
	v_mul_f32_e64 v132, |v125|, s80
	v_exp_f32_e32 v193, v132
	v_mul_f32_e64 v77, |v131|, s80
	v_log_f32_e32 v75, v75
	v_exp_f32_e32 v77, v77
	v_mul_f32_e64 v79, |v128|, s80
	v_exp_f32_e32 v79, v79
	v_mul_f32_e32 v132, 0x3f317217, v75
	v_fma_f32 v132, v75, s10, -v132
	v_fmac_f32_e32 v132, 0x3377d1cf, v75
	v_fmac_f32_e32 v132, 0x3f317217, v75
	v_min_f32_e32 v130, 0, v130
	v_min_f32_e32 v131, 0, v131
	v_mov_b32_e32 v132, v132
	v_add_f32_e32 v75, 1.0, v77
	v_min_f32_e32 v128, 0, v128
	v_min_f32_e32 v129, 0, v129
	v_log_f32_e32 v75, v75
	v_lshlrev_b32_e32 v194, 16, v46
	v_and_b32_e32 v195, 0xffff0000, v46
	v_lshlrev_b32_e32 v196, 16, v47
	v_mul_f32_e32 v77, 0x3f317217, v75
	v_fma_f32 v77, v75, s10, -v77
	v_fmac_f32_e32 v77, 0x3377d1cf, v75
	v_fmac_f32_e32 v77, 0x3f317217, v75
	v_and_b32_e32 v197, 0xffff0000, v47
	v_lshlrev_b32_e32 v46, 16, v42
	v_mov_b32_e32 v133, v77
	v_add_f32_e32 v75, 1.0, v79
	v_lshlrev_b32_e32 v79, 16, v45
	v_and_b32_e32 v42, 0xffff0000, v42
	v_log_f32_e32 v75, v75
	v_lshlrev_b32_e32 v47, 16, v43
	v_and_b32_e32 v43, 0xffff0000, v43
	v_mul_f32_e32 v203, 0x3e000000, v42
	v_mul_f32_e32 v77, 0x3f317217, v75
	v_fma_f32 v77, v75, s10, -v77
	v_fmac_f32_e32 v77, 0x3377d1cf, v75
	v_fmac_f32_e32 v77, 0x3f317217, v75
	v_mul_f32_e32 v205, 0x3e000000, v43
	v_min_f32_e32 v126, 0, v126
	v_mov_b32_e32 v188, v77
	v_add_f32_e32 v75, 1.0, v187
	v_and_b32_e32 v187, 0xffff0000, v45
	v_lshlrev_b32_e32 v45, 16, v41
	v_log_f32_e32 v75, v75
	v_and_b32_e32 v41, 0xffff0000, v41
	v_mul_f32_e32 v201, 0x3e000000, v41
	v_min_f32_e32 v127, 0, v127
	v_mul_f32_e32 v77, 0x3f317217, v75
	v_fma_f32 v77, v75, s10, -v77
	v_fmac_f32_e32 v77, 0x3377d1cf, v75
	v_fmac_f32_e32 v77, 0x3f317217, v75
	v_mul_f32_e32 v200, 0x3e000000, v45
	v_min_f32_e32 v124, 0, v124
	v_mov_b32_e32 v189, v77
	v_add_f32_e32 v75, 1.0, v190
	v_pk_add_f32 v[42:43], v[128:129], v[188:189] neg_lo:[0,1] neg_hi:[0,1]
	v_min_f32_e32 v125, 0, v125
	v_log_f32_e32 v75, v75
	v_pk_mul_f32 v[42:43], v[42:43], s[92:93] op_sel_hi:[1,0]
	v_mul_f32_e32 v202, 0x3e000000, v46
	v_cndmask_b32_e64 v42, 0, v42, s[42:43]
	v_mul_f32_e32 v77, 0x3f317217, v75
	v_fma_f32 v77, v75, s10, -v77
	v_fmac_f32_e32 v77, 0x3377d1cf, v75
	v_fmac_f32_e32 v77, 0x3f317217, v75
	v_add_f32_dpp v42, v42, v42 row_shr:1 row_mask:0xf bank_mask:0xf bound_ctrl:1
	v_cndmask_b32_e64 v43, 0, v43, s[42:43]
	v_mov_b32_e32 v190, v77
	v_add_f32_e32 v75, 1.0, v191
	v_add_f32_dpp v42, v42, v42 row_shr:2 row_mask:0xf bank_mask:0xf bound_ctrl:1
	v_add_f32_dpp v43, v43, v43 row_shr:1 row_mask:0xf bank_mask:0xf bound_ctrl:1
	v_log_f32_e32 v75, v75
	v_add_f32_dpp v42, v42, v42 row_shr:4 row_mask:0xf bank_mask:0xf bound_ctrl:1
	v_add_f32_dpp v43, v43, v43 row_shr:2 row_mask:0xf bank_mask:0xf bound_ctrl:1
	v_mul_f32_e32 v204, 0x3e000000, v47
	v_mul_f32_e32 v77, 0x3f317217, v75
	v_fma_f32 v77, v75, s10, -v77
	v_fmac_f32_e32 v77, 0x3377d1cf, v75
	v_fmac_f32_e32 v77, 0x3f317217, v75
	v_add_f32_dpp v42, v42, v42 row_shr:8 row_mask:0xf bank_mask:0xf bound_ctrl:1
	v_add_f32_dpp v43, v43, v43 row_shr:4 row_mask:0xf bank_mask:0xf bound_ctrl:1
	v_mov_b32_e32 v191, v77
	v_add_f32_e32 v75, 1.0, v192
	v_add_f32_dpp v43, v43, v43 row_shr:8 row_mask:0xf bank_mask:0xf bound_ctrl:1
	v_cndmask_b32_e64 v128, 0, v187, s[42:43]
	v_log_f32_e32 v75, v75
	v_cndmask_b32_e64 v187, 0, v196, s[42:43]
	v_cndmask_b32_e64 v189, 0, v197, s[42:43]
	v_cndmask_b32_e64 v129, 0, v202, s[42:43]
	v_mul_f32_e32 v77, 0x3f317217, v75
	v_fma_f32 v77, v75, s10, -v77
	v_fmac_f32_e32 v77, 0x3377d1cf, v75
	v_fmac_f32_e32 v77, 0x3f317217, v75
	v_cndmask_b32_e64 v188, 0, v205, s[42:43]
	v_cndmask_b32_e64 v79, 0, v79, s[42:43]
	v_mov_b32_e32 v192, v77
	v_add_f32_e32 v75, 1.0, v193
	s_nop 1
	v_log_f32_e32 v75, v75
	s_nop 0
	v_mul_f32_e32 v77, 0x3f317217, v75
	v_fma_f32 v77, v75, s10, -v77
	v_fmac_f32_e32 v77, 0x3377d1cf, v75
	v_fmac_f32_e32 v77, 0x3f317217, v75
	s_nop 1
	v_mov_b32_e32 v193, v77
	v_lshlrev_b32_e32 v75, 16, v44
	v_and_b32_e32 v77, 0xffff0000, v44
	v_lshlrev_b32_e32 v44, 16, v40
	v_and_b32_e32 v40, 0xffff0000, v40
	v_mul_f32_e32 v199, 0x3e000000, v40
	v_pk_add_f32 v[40:41], v[130:131], v[132:133] neg_lo:[0,1] neg_hi:[0,1]
	v_mul_f32_e32 v198, 0x3e000000, v44
	v_pk_mul_f32 v[40:41], v[40:41], s[92:93] op_sel_hi:[1,0]
	v_pk_add_f32 v[44:45], v[126:127], v[190:191] neg_lo:[0,1] neg_hi:[0,1]
	v_cndmask_b32_e64 v40, 0, v40, s[42:43]
	v_cndmask_b32_e64 v41, 0, v41, s[42:43]
	s_nop 0
	v_add_f32_dpp v40, v40, v40 row_shr:1 row_mask:0xf bank_mask:0xf bound_ctrl:1
	v_add_f32_dpp v41, v41, v41 row_shr:1 row_mask:0xf bank_mask:0xf bound_ctrl:1
	v_pk_mul_f32 v[44:45], v[44:45], s[92:93] op_sel_hi:[1,0]
	v_add_f32_dpp v40, v40, v40 row_shr:2 row_mask:0xf bank_mask:0xf bound_ctrl:1
	v_add_f32_dpp v41, v41, v41 row_shr:2 row_mask:0xf bank_mask:0xf bound_ctrl:1
	v_cndmask_b32_e64 v44, 0, v44, s[42:43]
	v_add_f32_dpp v40, v40, v40 row_shr:4 row_mask:0xf bank_mask:0xf bound_ctrl:1
	v_add_f32_dpp v41, v41, v41 row_shr:4 row_mask:0xf bank_mask:0xf bound_ctrl:1
	v_add_f32_dpp v44, v44, v44 row_shr:1 row_mask:0xf bank_mask:0xf bound_ctrl:1
	v_add_f32_dpp v40, v40, v40 row_shr:8 row_mask:0xf bank_mask:0xf bound_ctrl:1
	v_add_f32_dpp v41, v41, v41 row_shr:8 row_mask:0xf bank_mask:0xf bound_ctrl:1
	v_pk_add_f32 v[46:47], v[124:125], v[192:193] neg_lo:[0,1] neg_hi:[0,1]
	v_add_f32_dpp v40, v40, v40 row_bcast:15 row_mask:0xa bank_mask:0xf
	v_cndmask_b32_e64 v45, 0, v45, s[42:43]
	v_add_f32_dpp v44, v44, v44 row_shr:2 row_mask:0xf bank_mask:0xf bound_ctrl:1
	v_add_f32_dpp v41, v41, v41 row_bcast:15 row_mask:0xa bank_mask:0xf
	v_pk_mul_f32 v[46:47], v[46:47], s[92:93] op_sel_hi:[1,0]
	v_add_f32_dpp v45, v45, v45 row_shr:1 row_mask:0xf bank_mask:0xf bound_ctrl:1
	v_add_f32_dpp v42, v42, v42 row_bcast:15 row_mask:0xa bank_mask:0xf
	v_add_f32_dpp v44, v44, v44 row_shr:4 row_mask:0xf bank_mask:0xf bound_ctrl:1
	v_cndmask_b32_e64 v46, 0, v46, s[42:43]
	v_add_f32_dpp v45, v45, v45 row_shr:2 row_mask:0xf bank_mask:0xf bound_ctrl:1
	v_add_f32_dpp v44, v44, v44 row_shr:8 row_mask:0xf bank_mask:0xf bound_ctrl:1
	v_add_f32_dpp v43, v43, v43 row_bcast:15 row_mask:0xa bank_mask:0xf
	v_add_f32_dpp v46, v46, v46 row_shr:1 row_mask:0xf bank_mask:0xf bound_ctrl:1
	v_add_f32_dpp v45, v45, v45 row_shr:4 row_mask:0xf bank_mask:0xf bound_ctrl:1
	v_cndmask_b32_e64 v47, 0, v47, s[42:43]
	v_add_f32_dpp v46, v46, v46 row_shr:2 row_mask:0xf bank_mask:0xf bound_ctrl:1
	v_add_f32_dpp v45, v45, v45 row_shr:8 row_mask:0xf bank_mask:0xf bound_ctrl:1
	v_add_f32_dpp v44, v44, v44 row_bcast:15 row_mask:0xa bank_mask:0xf
	v_add_f32_dpp v47, v47, v47 row_shr:1 row_mask:0xf bank_mask:0xf bound_ctrl:1
	v_add_f32_dpp v46, v46, v46 row_shr:4 row_mask:0xf bank_mask:0xf bound_ctrl:1
	s_nop 0
	v_add_f32_dpp v47, v47, v47 row_shr:2 row_mask:0xf bank_mask:0xf bound_ctrl:1
	v_add_f32_dpp v46, v46, v46 row_shr:8 row_mask:0xf bank_mask:0xf bound_ctrl:1
	v_add_f32_dpp v45, v45, v45 row_bcast:15 row_mask:0xa bank_mask:0xf
	v_add_f32_dpp v47, v47, v47 row_shr:4 row_mask:0xf bank_mask:0xf bound_ctrl:1
	v_max_f32_e32 v40, 0xc2a00000, v40
	s_nop 0
	v_add_f32_dpp v47, v47, v47 row_shr:8 row_mask:0xf bank_mask:0xf bound_ctrl:1
	v_add_f32_dpp v46, v46, v46 row_bcast:15 row_mask:0xa bank_mask:0xf
	v_mul_f32_e32 v40, 0x3fb8aa3b, v40
	v_cndmask_b32_e64 v130, 0, v194, s[42:43]
	v_add_f32_dpp v47, v47, v47 row_bcast:15 row_mask:0xa bank_mask:0xf
	v_exp_f32_e32 v190, v40
	v_max_f32_e32 v40, 0xc2a00000, v41
	v_mul_f32_e32 v40, 0x3fb8aa3b, v40
	v_exp_f32_e32 v191, v40
	v_max_f32_e32 v40, 0xc2a00000, v42
	v_mul_f32_e32 v40, 0x3fb8aa3b, v40
	v_exp_f32_e32 v192, v40
	v_max_f32_e32 v40, 0xc2a00000, v43
	v_mul_f32_e32 v40, 0x3fb8aa3b, v40
	v_exp_f32_e32 v193, v40
	v_max_f32_e32 v40, 0xc2a00000, v44
	v_mul_f32_e32 v40, 0x3fb8aa3b, v40
	v_exp_f32_e32 v194, v40
	v_max_f32_e32 v40, 0xc2a00000, v45
	v_mul_f32_e32 v40, 0x3fb8aa3b, v40
	v_cndmask_b32_e64 v132, 0, v195, s[42:43]
	v_exp_f32_e32 v195, v40
	v_max_f32_e32 v40, 0xc2a00000, v46
	v_mul_f32_e32 v40, 0x3fb8aa3b, v40
	v_exp_f32_e32 v196, v40
	v_max_f32_e32 v40, 0xc2a00000, v47
	v_mul_f32_e32 v40, 0x3fb8aa3b, v40
	v_exp_f32_e32 v197, v40
	ds_bpermute_b32 v40, v244, v190
	ds_bpermute_b32 v41, v244, v191
	ds_bpermute_b32 v42, v244, v192
	ds_bpermute_b32 v43, v244, v193
	ds_bpermute_b32 v44, v244, v194
	ds_bpermute_b32 v45, v244, v195
	ds_bpermute_b32 v46, v244, v196
	ds_bpermute_b32 v47, v244, v197
	v_cndmask_b32_e64 v124, 0, v198, s[42:43]
	v_cndmask_b32_e64 v125, 0, v199, s[42:43]
	v_cndmask_b32_e64 v126, 0, v200, s[42:43]
	v_cndmask_b32_e64 v127, 0, v201, s[42:43]
	v_cndmask_b32_e64 v131, 0, v203, s[42:43]
	v_cndmask_b32_e64 v133, 0, v204, s[42:43]
	v_rcp_f32_e32 v198, v190
	v_rcp_f32_e32 v199, v191
	v_rcp_f32_e32 v200, v192
	v_rcp_f32_e32 v201, v193
	v_rcp_f32_e32 v202, v194
	v_rcp_f32_e32 v203, v195
	v_rcp_f32_e32 v204, v196
	v_rcp_f32_e32 v205, v197
	v_cndmask_b32_e64 v75, 0, v75, s[42:43]
	v_cndmask_b32_e64 v77, 0, v77, s[42:43]
	v_mul_f32_e32 v124, v124, v190
	v_mul_f32_e32 v75, v75, v198
	v_mul_f32_e32 v125, v125, v191
	v_mul_f32_e32 v77, v77, v199
	v_mul_f32_e32 v126, v126, v192
	v_mul_f32_e32 v79, v79, v200
	v_mul_f32_e32 v127, v127, v193
	v_mul_f32_e32 v193, v128, v201
	v_mul_f32_e32 v128, v129, v194
	v_mul_f32_e32 v130, v130, v202
	v_mul_f32_e32 v129, v131, v195
	v_mul_f32_e32 v131, v132, v203
	v_mul_f32_e32 v187, v187, v204
	v_mul_f32_e32 v189, v189, v205
	s_waitcnt lgkmcnt(0)
	v_mul_f32_e32 v194, v130, v44
	v_mul_f32_e32 v132, v131, v45
	v_cvt_pk_bf16_f32 v124, v124, v125
	v_cvt_pk_bf16_f32 v125, v126, v127
	v_cvt_pk_bf16_f32 v126, v128, v129
	v_cvt_pk_bf16_f32 v128, v75, v77
	v_cvt_pk_bf16_f32 v129, v79, v193
	v_cvt_pk_bf16_f32 v130, v130, v131
	v_cvt_pk_bf16_f32 v131, v187, v189
	v_mul_f32_e32 v133, v133, v196
	v_mul_f32_e32 v188, v188, v197
	v_cvt_pk_bf16_f32 v127, v133, v188
	s_nop 1
	v_mfma_f32_32x32x16_bf16 v[2:17], v[128:131], v[124:127], v[2:17]
	v_mul_f32_e32 v190, v40, v75
	v_xor_b32_e32 v75, v71, v168
	v_mul_f32_e32 v191, v77, v41
	v_lshl_add_u32 v75, v75, 4, v167
	v_mul_f32_e32 v192, v79, v42
	v_mul_f32_e32 v198, v193, v43
	ds_write_b128 v75, v[124:127] offset:20480
	v_cvt_pk_bf16_f32 v75, v190, v191
	ds_write_b16 v73, v75
	ds_write_b16_d16_hi v73, v75 offset:64
	v_cvt_pk_bf16_f32 v75, v192, v198
	v_mul_f32_e32 v195, v187, v46
	v_mul_f32_e32 v196, v189, v47
	ds_write_b16 v73, v75 offset:128
	ds_write_b16_d16_hi v73, v75 offset:192
	v_cvt_pk_bf16_f32 v75, v194, v132
	ds_write_b16 v73, v75 offset:256
	ds_write_b16_d16_hi v73, v75 offset:320
	v_cvt_pk_bf16_f32 v75, v195, v196
	ds_write_b16 v73, v75 offset:384
	ds_write_b16_d16_hi v73, v75 offset:448
	s_and_saveexec_b64 s[0:1], s[4:5]
	s_cbranch_execz .LBB0_562
	v_add_u32_e32 v75, s57, v183
	ds_write_b128 v75, v[40:43]
	ds_write_b128 v75, v[44:47] offset:16
	s_branch .LBB0_562
